# v31 + 10 provably satisfied lgkmcnt waits removed from the attention QK phases, run 1
# baseline (speedup 1.0000x reference)
.LBB0_375:
	v_lshl_add_u32 v154, s60, 14, v241
	ds_read_b64_tr_b16 v[150:151], v154 offset:24576
	ds_read_b64_tr_b16 v[152:153], v154 offset:25088
	v_add_f32_e32 v106, v82, v83
	v_add_f32_e32 v106, v84, v106
	v_add_f32_e32 v106, v85, v106
	v_add_f32_e32 v106, v86, v106
	v_add_f32_e32 v106, v87, v106
	v_cvt_pk_bf16_f32 v174, v82, v83
	v_cvt_pk_bf16_f32 v175, v84, v85
	v_mfma_f32_32x32x16_bf16 v[114:129], v[102:105], v[190:193], 0
	ds_read_b64_tr_b16 v[82:83], v154 offset:28672
	ds_read_b64_tr_b16 v[84:85], v154 offset:29184
	v_add_f32_e32 v102, v88, v106
	v_add_f32_e32 v102, v89, v102
	v_add_f32_e32 v102, v90, v102
	v_add_f32_e32 v155, v91, v102
	v_mfma_f32_32x32x16_bf16 v[98:113], v[98:101], v[190:193], 0
	v_cvt_pk_bf16_f32 v176, v86, v87
	v_cvt_pk_bf16_f32 v177, v88, v89
	ds_read_b64_tr_b16 v[86:87], v154 offset:32768
	ds_read_b64_tr_b16 v[88:89], v154 offset:33280
	v_add_f32_e32 v155, v92, v155
	v_add_f32_e32 v155, v93, v155
	v_add_f32_e32 v155, v94, v155
	v_add_f32_e32 v155, v95, v155
	v_cvt_pk_bf16_f32 v170, v90, v91
	v_cvt_pk_bf16_f32 v171, v92, v93
	v_mfma_f32_32x32x16_bf16 v[114:129], v[198:201], v[186:189], v[114:129]
	ds_read_b64_tr_b16 v[90:91], v154 offset:36864
	ds_read_b64_tr_b16 v[92:93], v154 offset:37376
	v_mfma_f32_32x32x16_bf16 v[98:113], v[142:145], v[186:189], v[98:113]
	v_add_f32_e32 v155, v96, v155
	v_add_f32_e32 v155, v97, v155
	v_add_f32_e32 v155, v66, v155
	v_add_f32_e32 v155, v67, v155
	v_cvt_pk_bf16_f32 v172, v94, v95
	v_cvt_pk_bf16_f32 v173, v96, v97
	s_nop 0
	v_add_f32_e32 v94, v68, v155
	v_add_f32_e32 v94, v69, v94
	v_add_f32_e32 v94, v70, v94
	v_add_f32_e32 v94, v71, v94
	v_cvt_pk_bf16_f32 v166, v66, v67
	v_cvt_pk_bf16_f32 v167, v68, v69
	v_mfma_f32_32x32x16_bf16 v[114:129], v[194:197], v[182:185], v[114:129]
	v_mfma_f32_32x32x16_bf16 v[98:113], v[134:137], v[182:185], v[98:113]
	v_add_f32_e32 v66, v72, v94
	v_add_f32_e32 v66, v73, v66
	v_add_f32_e32 v66, v74, v66
	v_add_f32_e32 v66, v75, v66
	v_cvt_pk_bf16_f32 v168, v70, v71
	v_cvt_pk_bf16_f32 v169, v72, v73
	s_nop 0
	v_add_f32_e32 v66, v76, v66
	v_add_f32_e32 v66, v77, v66
	v_add_f32_e32 v66, v78, v66
	v_add_f32_e32 v66, v79, v66
	v_cvt_pk_bf16_f32 v162, v74, v75
	v_cvt_pk_bf16_f32 v163, v76, v77
	v_mfma_f32_32x32x16_bf16 v[114:129], v[138:141], v[178:181], v[114:129]
	v_mfma_f32_32x32x16_bf16 v[98:113], v[130:133], v[178:181], v[98:113]
	v_add_f32_e32 v66, v80, v66
	v_add_f32_e32 v66, v81, v66
	v_add_f32_e32 v66, 0, v66
	v_cvt_pk_bf16_f32 v164, v78, v79
	v_cvt_pk_bf16_f32 v165, v80, v81
	s_lshl_b32 s12, s7, 13
	s_add_i32 s12, s12, s91
	v_add_f32_e32 v198, v202, v66
	v_lshl_add_u64 v[66:67], v[146:147], 0, s[24:25]
	s_mov_b32 s13, m0
	s_mov_b32 m0, s12
	s_nop 0
	global_load_lds_dwordx4 v[66:67], off
	s_mov_b32 m0, s13
	s_lshl_b32 s12, s0, 14
	v_lshl_add_u64 v[66:67], v[148:149], 0, s[4:5]
	s_add_i32 s12, s12, s92
	s_mov_b32 s13, m0
	s_mov_b32 m0, s12
	s_nop 0
	global_load_lds_dwordx4 v[66:67], off
	s_mov_b32 m0, s13
	v_lshl_add_u64 v[66:67], v[148:149], 0, s[8:9]
	s_addk_i32 s12, 0x2000
	s_mov_b32 s13, m0
	s_mov_b32 m0, s12
	s_nop 0
	global_load_lds_dwordx4 v[66:67], off
	s_mov_b32 m0, s13
	s_waitcnt lgkmcnt(6)
	v_mfma_f32_32x32x16_bf16 v[50:65], v[174:177], v[150:153], v[50:65]
	v_exp_f32_e32 v114, v114
	v_exp_f32_e32 v115, v115
	ds_read_b64_tr_b16 v[66:67], v154 offset:25600
	ds_read_b64_tr_b16 v[68:69], v154 offset:26112
	s_waitcnt lgkmcnt(6)
	v_mfma_f32_32x32x16_bf16 v[34:49], v[174:177], v[82:85], v[34:49]
	v_exp_f32_e32 v116, v116
	v_exp_f32_e32 v117, v117
	ds_read_b64_tr_b16 v[70:71], v154 offset:29696
	ds_read_b64_tr_b16 v[72:73], v154 offset:30208
	s_waitcnt lgkmcnt(6)
	v_mfma_f32_32x32x16_bf16 v[18:33], v[174:177], v[86:89], v[18:33]
	v_exp_f32_e32 v118, v118
	v_exp_f32_e32 v119, v119
	ds_read_b64_tr_b16 v[74:75], v154 offset:33792
	ds_read_b64_tr_b16 v[76:77], v154 offset:34304
	s_waitcnt lgkmcnt(6)
	v_mfma_f32_32x32x16_bf16 v[2:17], v[174:177], v[90:93], v[2:17]
	v_exp_f32_e32 v120, v120
	v_exp_f32_e32 v121, v121
	ds_read_b64_tr_b16 v[78:79], v154 offset:37888
	ds_read_b64_tr_b16 v[80:81], v154 offset:38400
	s_waitcnt lgkmcnt(6)
	v_mfma_f32_32x32x16_bf16 v[50:65], v[170:173], v[66:69], v[50:65]
	v_exp_f32_e32 v122, v122
	v_exp_f32_e32 v123, v123
	ds_read_b64_tr_b16 v[82:83], v154 offset:26624
	ds_read_b64_tr_b16 v[84:85], v154 offset:27136
	s_waitcnt lgkmcnt(6)
	v_mfma_f32_32x32x16_bf16 v[34:49], v[170:173], v[70:73], v[34:49]
	v_exp_f32_e32 v124, v124
	v_exp_f32_e32 v125, v125
	ds_read_b64_tr_b16 v[66:67], v154 offset:30720
	ds_read_b64_tr_b16 v[68:69], v154 offset:31232
	s_waitcnt lgkmcnt(6)
	v_mfma_f32_32x32x16_bf16 v[18:33], v[170:173], v[74:77], v[18:33]
	s_lshl_b32 s60, s0, 13
	v_exp_f32_e32 v126, v126
	v_exp_f32_e32 v127, v127
	v_add_u32_e32 v90, s60, v243
	ds_read_b128 v[70:73], v90
	ds_read_b128 v[130:133], v90 offset:512
	ds_read_b64_tr_b16 v[86:87], v154 offset:34816
	ds_read_b64_tr_b16 v[88:89], v154 offset:35328
	s_waitcnt lgkmcnt(8)
	v_mfma_f32_32x32x16_bf16 v[2:17], v[170:173], v[78:81], v[2:17]
	v_exp_f32_e32 v128, v128
	v_exp_f32_e32 v129, v129
	ds_read_b64_tr_b16 v[74:75], v154 offset:38912
	ds_read_b64_tr_b16 v[76:77], v154 offset:39424
	s_waitcnt lgkmcnt(8)
	v_mfma_f32_32x32x16_bf16 v[50:65], v[166:169], v[82:85], v[50:65]
	v_exp_f32_e32 v98, v98
	v_exp_f32_e32 v99, v99
	ds_read_b128 v[134:137], v90 offset:2048
	ds_read_b128 v[138:141], v90 offset:2560
	ds_read_b64_tr_b16 v[78:79], v154 offset:27648
	ds_read_b64_tr_b16 v[80:81], v154 offset:28160
	s_waitcnt lgkmcnt(10)
	v_mfma_f32_32x32x16_bf16 v[34:49], v[166:169], v[66:69], v[34:49]
	v_exp_f32_e32 v100, v100
	v_exp_f32_e32 v101, v101
	ds_read_b64_tr_b16 v[82:83], v154 offset:31744
	ds_read_b64_tr_b16 v[84:85], v154 offset:32256
	s_waitcnt lgkmcnt(8)
	v_mfma_f32_32x32x16_bf16 v[18:33], v[166:169], v[86:89], v[18:33]
	v_exp_f32_e32 v102, v102
	v_exp_f32_e32 v103, v103
	ds_read_b128 v[142:145], v90 offset:4096
	ds_read_b128 v[150:153], v90 offset:4608
	ds_read_b64_tr_b16 v[66:67], v154 offset:35840
	ds_read_b64_tr_b16 v[68:69], v154 offset:36352
	s_waitcnt lgkmcnt(10)
	v_mfma_f32_32x32x16_bf16 v[2:17], v[166:169], v[74:77], v[2:17]
	v_exp_f32_e32 v104, v104
	v_exp_f32_e32 v105, v105
	ds_read_b64_tr_b16 v[86:87], v154 offset:39936
	ds_read_b64_tr_b16 v[88:89], v154 offset:40448
	s_waitcnt lgkmcnt(8)
	v_mfma_f32_32x32x16_bf16 v[50:65], v[162:165], v[78:81], v[50:65]
	ds_read_b128 v[154:157], v90 offset:6144
	ds_read_b128 v[158:161], v90 offset:6656
	v_exp_f32_e32 v106, v106
	v_exp_f32_e32 v107, v107
	s_cmp_lg_u32 s98, 0
	s_cbranch_scc0 .Lst_e0
	s_waitcnt vmcnt(3) lgkmcnt(0)
	s_barrier

.Lst_b0:
	s_add_i32 s12, s0, 1
	s_cmp_lg_u32 s0, 2
	s_cselect_b32 s33, s12, 0
	v_lshl_add_u32 v244, s7, 14, v241
	ds_read_b64_tr_b16 v[194:195], v244 offset:24576
	ds_read_b64_tr_b16 v[196:197], v244 offset:25088
	v_mfma_f32_32x32x16_bf16 v[82:97], v[70:73], v[190:193], 0
	v_add_f32_e32 v66, v114, v115
	v_add_f32_e32 v66, v116, v66
	v_add_f32_e32 v66, v117, v66
	v_add_f32_e32 v66, v118, v66
	v_add_f32_e32 v66, v119, v66
	v_cvt_pk_bf16_f32 v174, v114, v115
	v_cvt_pk_bf16_f32 v175, v116, v117
	ds_read_b64_tr_b16 v[114:115], v244 offset:28672
	ds_read_b64_tr_b16 v[116:117], v244 offset:29184
	v_add_f32_e32 v66, v120, v66
	v_add_f32_e32 v66, v121, v66
	v_add_f32_e32 v66, v122, v66
	v_add_f32_e32 v162, v123, v66
	v_mfma_f32_32x32x16_bf16 v[66:81], v[130:133], v[190:193], 0
	v_cvt_pk_bf16_f32 v176, v118, v119
	v_cvt_pk_bf16_f32 v177, v120, v121
	ds_read_b64_tr_b16 v[118:119], v244 offset:32768
	ds_read_b64_tr_b16 v[120:121], v244 offset:33280
	v_mfma_f32_32x32x16_bf16 v[82:97], v[134:137], v[186:189], v[82:97]
	v_add_f32_e32 v130, v124, v162
	v_add_f32_e32 v130, v125, v130
	v_add_f32_e32 v130, v126, v130
	v_add_f32_e32 v130, v127, v130
	v_cvt_pk_bf16_f32 v170, v122, v123
	v_cvt_pk_bf16_f32 v171, v124, v125
	ds_read_b64_tr_b16 v[122:123], v244 offset:36864
	ds_read_b64_tr_b16 v[124:125], v244 offset:37376
	v_mfma_f32_32x32x16_bf16 v[66:81], v[138:141], v[186:189], v[66:81]
	v_add_f32_e32 v130, v128, v130
	v_add_f32_e32 v130, v129, v130
	v_add_f32_e32 v130, v98, v130
	v_add_f32_e32 v130, v99, v130
	v_cvt_pk_bf16_f32 v172, v126, v127
	v_cvt_pk_bf16_f32 v173, v128, v129
	v_mfma_f32_32x32x16_bf16 v[82:97], v[142:145], v[182:185], v[82:97]
	v_add_f32_e32 v126, v100, v130
	v_add_f32_e32 v126, v101, v126
	v_add_f32_e32 v126, v102, v126
	v_add_f32_e32 v126, v103, v126
	v_cvt_pk_bf16_f32 v166, v98, v99
	v_cvt_pk_bf16_f32 v167, v100, v101
	v_mfma_f32_32x32x16_bf16 v[66:81], v[150:153], v[182:185], v[66:81]
	v_add_f32_e32 v98, v104, v126
	v_add_f32_e32 v98, v105, v98
	v_add_f32_e32 v98, v106, v98
	v_add_f32_e32 v98, v107, v98
	v_cvt_pk_bf16_f32 v168, v102, v103
	v_cvt_pk_bf16_f32 v169, v104, v105
	v_mfma_f32_32x32x16_bf16 v[82:97], v[154:157], v[178:181], v[82:97]
	v_add_f32_e32 v98, v108, v98
	v_add_f32_e32 v98, v109, v98
	v_add_f32_e32 v98, v110, v98
	v_add_f32_e32 v98, v111, v98
	v_cvt_pk_bf16_f32 v162, v106, v107
	v_cvt_pk_bf16_f32 v163, v108, v109
	v_mfma_f32_32x32x16_bf16 v[66:81], v[158:161], v[178:181], v[66:81]
	v_add_f32_e32 v98, v112, v98
	v_add_f32_e32 v98, v113, v98
	v_add_f32_e32 v98, 0, v98
	v_cvt_pk_bf16_f32 v164, v110, v111
	v_cvt_pk_bf16_f32 v165, v112, v113
	s_add_i32 s7, s60, s91
	v_add_f32_e32 v202, v198, v98
	v_lshl_add_u64 v[98:99], v[146:147], 0, s[30:31]
	s_mov_b32 s12, m0
	s_mov_b32 m0, s7
	s_nop 0
	global_load_lds_dwordx4 v[98:99], off
	s_mov_b32 m0, s12
	s_lshl_b32 s7, s33, 14
	v_lshl_add_u64 v[106:107], v[148:149], 0, s[22:23]
	s_add_i32 s7, s7, s92
	s_mov_b32 s12, m0
	s_mov_b32 m0, s7
	s_nop 0
	global_load_lds_dwordx4 v[106:107], off
	s_mov_b32 m0, s12
	v_lshl_add_u64 v[98:99], v[148:149], 0, s[44:45]
	s_addk_i32 s7, 0x2000
	s_mov_b32 s12, m0
	s_mov_b32 m0, s7
	s_nop 0
	global_load_lds_dwordx4 v[98:99], off
	s_mov_b32 m0, s12
	s_waitcnt lgkmcnt(6)
	v_mfma_f32_32x32x16_bf16 v[50:65], v[174:177], v[194:197], v[50:65]
	v_exp_f32_e32 v82, v82
	v_exp_f32_e32 v83, v83
	ds_read_b64_tr_b16 v[98:99], v244 offset:25600
	ds_read_b64_tr_b16 v[100:101], v244 offset:26112
	s_waitcnt lgkmcnt(6)
	v_mfma_f32_32x32x16_bf16 v[34:49], v[174:177], v[114:117], v[34:49]
	v_exp_f32_e32 v84, v84
	v_exp_f32_e32 v85, v85
	ds_read_b64_tr_b16 v[102:103], v244 offset:29696
	ds_read_b64_tr_b16 v[104:105], v244 offset:30208
	s_waitcnt lgkmcnt(6)
	v_mfma_f32_32x32x16_bf16 v[18:33], v[174:177], v[118:121], v[18:33]
	v_exp_f32_e32 v86, v86
	v_exp_f32_e32 v87, v87
	ds_read_b64_tr_b16 v[108:109], v244 offset:33792
	ds_read_b64_tr_b16 v[110:111], v244 offset:34304
	s_waitcnt lgkmcnt(6)
	v_mfma_f32_32x32x16_bf16 v[2:17], v[174:177], v[122:125], v[2:17]
	v_exp_f32_e32 v88, v88
	v_exp_f32_e32 v89, v89
	ds_read_b64_tr_b16 v[112:113], v244 offset:37888
	ds_read_b64_tr_b16 v[114:115], v244 offset:38400
	s_waitcnt lgkmcnt(6)
	v_mfma_f32_32x32x16_bf16 v[50:65], v[170:173], v[98:101], v[50:65]
	v_exp_f32_e32 v90, v90
	v_exp_f32_e32 v91, v91
	ds_read_b64_tr_b16 v[116:117], v244 offset:26624
	ds_read_b64_tr_b16 v[118:119], v244 offset:27136
	s_waitcnt lgkmcnt(6)
	v_mfma_f32_32x32x16_bf16 v[34:49], v[170:173], v[102:105], v[34:49]
	v_exp_f32_e32 v92, v92
	v_exp_f32_e32 v93, v93
	ds_read_b64_tr_b16 v[120:121], v244 offset:30720
	ds_read_b64_tr_b16 v[122:123], v244 offset:31232
	s_waitcnt lgkmcnt(6)
	v_mfma_f32_32x32x16_bf16 v[18:33], v[170:173], v[108:111], v[18:33]
	v_exp_f32_e32 v94, v94
	v_exp_f32_e32 v95, v95
	v_lshl_add_u32 v128, s33, 13, v243
	ds_read_b128 v[102:105], v128
	ds_read_b128 v[98:101], v128 offset:512
	ds_read_b64_tr_b16 v[124:125], v244 offset:34816
	ds_read_b64_tr_b16 v[126:127], v244 offset:35328
	s_waitcnt lgkmcnt(8)
	v_mfma_f32_32x32x16_bf16 v[2:17], v[170:173], v[112:115], v[2:17]
	v_exp_f32_e32 v96, v96
	v_exp_f32_e32 v97, v97
	ds_read_b64_tr_b16 v[108:109], v244 offset:38912
	ds_read_b64_tr_b16 v[110:111], v244 offset:39424
	s_waitcnt lgkmcnt(8)
	v_mfma_f32_32x32x16_bf16 v[50:65], v[166:169], v[116:119], v[50:65]
	v_exp_f32_e32 v66, v66
	v_exp_f32_e32 v67, v67
	ds_read_b128 v[198:201], v128 offset:2048
	ds_read_b128 v[142:145], v128 offset:2560
	ds_read_b64_tr_b16 v[112:113], v244 offset:27648
	ds_read_b64_tr_b16 v[114:115], v244 offset:28160
	s_waitcnt lgkmcnt(10)
	v_mfma_f32_32x32x16_bf16 v[34:49], v[166:169], v[120:123], v[34:49]
	v_exp_f32_e32 v68, v68
	v_exp_f32_e32 v69, v69
	ds_read_b64_tr_b16 v[116:117], v244 offset:31744
	ds_read_b64_tr_b16 v[118:119], v244 offset:32256
	s_waitcnt lgkmcnt(8)
	v_mfma_f32_32x32x16_bf16 v[18:33], v[166:169], v[124:127], v[18:33]
	v_exp_f32_e32 v70, v70
	v_exp_f32_e32 v71, v71
	ds_read_b128 v[194:197], v128 offset:4096
	ds_read_b128 v[134:137], v128 offset:4608
	ds_read_b64_tr_b16 v[120:121], v244 offset:35840
	ds_read_b64_tr_b16 v[122:123], v244 offset:36352
	s_waitcnt lgkmcnt(10)
	v_mfma_f32_32x32x16_bf16 v[2:17], v[166:169], v[108:111], v[2:17]
	v_exp_f32_e32 v72, v72
	v_exp_f32_e32 v73, v73
	ds_read_b64_tr_b16 v[124:125], v244 offset:39936
	ds_read_b64_tr_b16 v[126:127], v244 offset:40448
	s_waitcnt lgkmcnt(8)
	v_mfma_f32_32x32x16_bf16 v[50:65], v[162:165], v[112:115], v[50:65]
	ds_read_b128 v[138:141], v128 offset:6144
	ds_read_b128 v[130:133], v128 offset:6656
	v_exp_f32_e32 v74, v74
	v_exp_f32_e32 v75, v75
	s_cmp_lg_u32 s98, 0
	s_cbranch_scc0 .Lst_e1
	s_waitcnt vmcnt(3) lgkmcnt(0)
	s_barrier
